# phase 0 x-norm row loop hand-written with two rows in flight (partly rolled), numerics as the compiler's expansion
# speedup vs baseline: 1.0050x; 1.0050x over previous
; __device__ __forceinline__ unsigned pk2(float lo, float hi) { f32x2 v = {lo, hi}; bf16x2_t b = __builtin_convertvector(v, bf16x2_t); return __builtin_bit_cast(unsigned, b); }
; __device__ __forceinline__ float wave_sum(float v) { return wave_sum_fast(v); }
;     __device__ __forceinline__ const float* in(int i) const { return (const float*)ptr(i); }
;     __device__ __forceinline__ unsigned char* ws() const { return (unsigned char*)ptr(37); }
; #define ws (p.ws())
; __device__ __forceinline__ void rms_row_to_bf16(const float* xrow, const float* g, bf16_t* orow, int lane) {
;     const f32x4* xr = (const f32x4*)xrow + lane; const f32x4* gr = (const f32x4*)g + lane;
;     f32x4 v[4]; float s = 0.f;
; #pragma unroll
;     for (int j = 0; j < 4; ++j) { v[j] = xr[64 * j]; s += (v[j].x * v[j].x + v[j].y * v[j].y) + (v[j].z * v[j].z + v[j].w * v[j].w); }
;     const float rs = 1.f / sqrtf(wave_sum(s) * (1.f / DM) + EPS);
;     u32x2* o8 = (u32x2*)orow + lane;
; #pragma unroll
;     for (int j = 0; j < 4; ++j) { const f32x4 gg = gr[64 * j]; u32x2 w; w.x = pk2(v[j].x * rs * gg.x, v[j].y * rs * gg.y); w.y = pk2(v[j].z * rs * gg.z, v[j].w * rs * gg.w); o8[64 * j] = w; }
; __device__ __forceinline__ void phase_prologue(const Ctx& p, LAS unsigned char* lds) {
;     ...
;     bf16_t* XN = (bf16_t*)(ws + WS_XN);
;     {   f32x4 g4[4], v[4], v2[4];
; #pragma unroll
;         for (int j = 0; j < 4; ++j) g4[j] = ((const f32x4*)p.in(6))[lane + 64 * j];
;         if (gw < MR) {
; #pragma unroll
;             for (int j = 0; j < 4; ++j) v[j] = ((const f32x4*)xrow_ptr(p, gw))[lane + 64 * j]; }
;         for (int m = gw; m < MP; m += NGW) {
;             const int mn = m + NGW;
;             if (mn < MR) {
; #pragma unroll
;                 for (int j = 0; j < 4; ++j) v2[j] = ((const f32x4*)xrow_ptr(p, mn))[lane + 64 * j]; }
;             u32x2* o8 = (u32x2*)(XN + (size_t)m * DM) + lane;
;             if (m < MR) {
;                 float sq = 0.f;
; #pragma unroll
;                 for (int j = 0; j < 4; ++j) sq += (v[j].x * v[j].x + v[j].y * v[j].y) + (v[j].z * v[j].z + v[j].w * v[j].w);
;                 const float rs = 1.f / sqrtf(wave_sum(sq) * (1.f / DM) + EPS);
; #pragma unroll
;                 for (int j = 0; j < 4; ++j) { u32x2 w; w.x = pk2(v[j].x * rs * g4[j].x, v[j].y * rs * g4[j].y); w.y = pk2(v[j].z * rs * g4[j].z, v[j].w * rs * g4[j].w); o8[64 * j] = w; }
.LBB0_25:
	v_mov_b32_e32 v0, 0x23400
	v_mov_b32_e32 v1, 0x23430
	ds_read_b128 v[2:5], v0
	ds_read_b64 v[6:7], v1
	v_and_b32_e32 v0, 63, v180
	v_lshlrev_b32_e32 v144, 4, v0
	v_lshlrev_b32_e32 v145, 3, v0
	v_mov_b32_e32 v146, 0x358637bd
	v_mov_b32_e32 v147, 0x260
	s_mov_b32 s33, 0xf800000
	s_waitcnt lgkmcnt(0)
	v_readfirstlane_b32 s14, v2
	v_readfirstlane_b32 s15, v3
	v_readfirstlane_b32 s16, v4
	v_readfirstlane_b32 s17, v5
	v_readfirstlane_b32 s18, v6
	v_readfirstlane_b32 s19, v7
	s_nop 4
	global_load_dwordx4 v[128:131], v144, s[18:19] offset:0
	global_load_dwordx4 v[132:135], v144, s[18:19] offset:1024
	global_load_dwordx4 v[136:139], v144, s[18:19] offset:2048
	global_load_dwordx4 v[140:143], v144, s[18:19] offset:3072
	s_lshl_b32 s2, s10, 12
	s_add_u32 s24, s14, s2
	s_addc_u32 s25, s15, 0
	s_lshl_b32 s2, s10, 11
	s_add_u32 s42, s12, s2
	s_addc_u32 s43, s13, 0
	s_add_u32 s42, s42, 0x3200000
	s_addc_u32 s43, s43, 0
	global_load_dwordx4 v[0:3], v144, s[24:25] offset:0
	global_load_dwordx4 v[4:7], v144, s[24:25] offset:1024
	global_load_dwordx4 v[8:11], v144, s[24:25] offset:2048
	global_load_dwordx4 v[12:15], v144, s[24:25] offset:3072
	s_add_u32 s24, s24, 0x800000
	s_addc_u32 s25, s25, 0
	global_load_dwordx4 v[16:19], v144, s[24:25] offset:0
	global_load_dwordx4 v[20:23], v144, s[24:25] offset:1024
	global_load_dwordx4 v[24:27], v144, s[24:25] offset:2048
	global_load_dwordx4 v[28:31], v144, s[24:25] offset:3072
	s_add_u32 s24, s24, 0x800000
	s_addc_u32 s25, s25, 0
	s_waitcnt vmcnt(4)
	v_mul_f32_e32 v96, v1, v1
	v_mul_f32_e32 v98, v3, v3
	v_fmac_f32_e32 v96, v0, v0
	v_fmac_f32_e32 v98, v2, v2
	v_add_f32_e32 v96, v96, v98
	v_mul_f32_e32 v97, v5, v5
	v_mul_f32_e32 v98, v7, v7
	v_fmac_f32_e32 v97, v4, v4
	v_fmac_f32_e32 v98, v6, v6
	v_add_f32_e32 v97, v97, v98
	v_add_f32_e32 v96, v97, v96
	v_mul_f32_e32 v97, v9, v9
	v_mul_f32_e32 v98, v11, v11
	v_fmac_f32_e32 v97, v8, v8
	v_fmac_f32_e32 v98, v10, v10
	v_add_f32_e32 v97, v97, v98
	v_add_f32_e32 v96, v97, v96
	v_mul_f32_e32 v97, v13, v13
	v_mul_f32_e32 v98, v15, v15
	v_fmac_f32_e32 v97, v12, v12
	v_fmac_f32_e32 v98, v14, v14
	v_add_f32_e32 v97, v97, v98
	v_add_f32_e32 v96, v97, v96
	s_nop 1
	v_add_f32_dpp v96, v96, v96 quad_perm:[1,0,3,2] row_mask:0xf bank_mask:0xf bound_ctrl:1
	s_nop 1
	v_add_f32_dpp v96, v96, v96 quad_perm:[2,3,0,1] row_mask:0xf bank_mask:0xf bound_ctrl:1
	s_nop 1
	v_add_f32_dpp v96, v96, v96 row_half_mirror row_mask:0xf bank_mask:0xf bound_ctrl:1
	s_nop 1
	v_add_f32_dpp v96, v96, v96 row_mirror row_mask:0xf bank_mask:0xf bound_ctrl:1
	v_mov_b32_e32 v97, v96
	s_nop 1
	v_permlane16_swap_b32_e32 v96, v97
	v_add_f32_e32 v96, v96, v97
	v_mov_b32_e32 v97, v96
	s_nop 1
	v_permlane32_swap_b32_e32 v96, v97
	v_add_f32_e32 v96, v96, v97
	v_fmamk_f32 v96, v96, 0x3a800000, v146
	v_mul_f32_e32 v97, 0x4f800000, v96
	v_cmp_gt_f32_e32 vcc, s33, v96
	s_nop 1
	v_cndmask_b32_e32 v96, v96, v97, vcc
	v_sqrt_f32_e32 v97, v96
	s_nop 0
	v_add_u32_e32 v98, -1, v97
	v_fma_f32 v99, -v98, v97, v96
	v_cmp_ge_f32_e64 s[4:5], 0, v99
	v_add_u32_e32 v99, 1, v97
	s_nop 0
	v_cndmask_b32_e64 v98, v97, v98, s[4:5]
	v_fma_f32 v97, -v99, v97, v96
	v_cmp_lt_f32_e64 s[4:5], 0, v97
	s_nop 1
	v_cndmask_b32_e64 v97, v98, v99, s[4:5]
	v_mul_f32_e32 v98, 0x37800000, v97
	v_cndmask_b32_e32 v97, v97, v98, vcc
	v_cmp_class_f32_e32 vcc, v96, v147
	s_nop 1
	v_cndmask_b32_e32 v96, v97, v96, vcc
	v_div_scale_f32 v97, s[4:5], v96, v96, 1.0
	v_rcp_f32_e32 v98, v97
	s_nop 0
	v_fma_f32 v99, -v97, v98, 1.0
	v_fmac_f32_e32 v98, v99, v98
	v_div_scale_f32 v99, vcc, 1.0, v96, 1.0
	v_mul_f32_e32 v100, v99, v98
	v_fma_f32 v101, -v97, v100, v99
	v_fmac_f32_e32 v100, v101, v98
	v_fma_f32 v97, -v97, v100, v99
	v_div_fmas_f32 v97, v97, v98, v100
	v_div_fixup_f32 v96, v97, v96, 1.0
	v_mul_f32_e32 v0, v0, v96
	v_mul_f32_e32 v1, v1, v96
	v_mul_f32_e32 v2, v2, v96
	v_mul_f32_e32 v3, v3, v96
	v_mul_f32_e32 v4, v4, v96
	v_mul_f32_e32 v5, v5, v96
	v_mul_f32_e32 v6, v6, v96
	v_mul_f32_e32 v7, v7, v96
	v_mul_f32_e32 v8, v8, v96
	v_mul_f32_e32 v9, v9, v96
	v_mul_f32_e32 v10, v10, v96
	v_mul_f32_e32 v11, v11, v96
	v_mul_f32_e32 v12, v12, v96
	v_mul_f32_e32 v13, v13, v96
	v_mul_f32_e32 v14, v14, v96
	v_mul_f32_e32 v15, v15, v96
	v_mul_f32_e32 v0, v128, v0
	v_mul_f32_e32 v1, v129, v1
	v_mul_f32_e32 v2, v130, v2
	v_mul_f32_e32 v3, v131, v3
	v_mul_f32_e32 v4, v132, v4
	v_mul_f32_e32 v5, v133, v5
	v_mul_f32_e32 v6, v134, v6
	v_mul_f32_e32 v7, v135, v7
	v_mul_f32_e32 v8, v136, v8
	v_mul_f32_e32 v9, v137, v9
	v_mul_f32_e32 v10, v138, v10
	v_mul_f32_e32 v11, v139, v11
	v_mul_f32_e32 v12, v140, v12
	v_mul_f32_e32 v13, v141, v13
	v_mul_f32_e32 v14, v142, v14
	v_mul_f32_e32 v15, v143, v15
	v_cvt_pk_bf16_f32 v148, v0, v1
	v_cvt_pk_bf16_f32 v149, v2, v3
	global_store_dwordx2 v145, v[148:149], s[42:43] offset:0
	v_cvt_pk_bf16_f32 v150, v4, v5
	v_cvt_pk_bf16_f32 v151, v6, v7
	global_store_dwordx2 v145, v[150:151], s[42:43] offset:512
	v_cvt_pk_bf16_f32 v152, v8, v9
	v_cvt_pk_bf16_f32 v153, v10, v11
	global_store_dwordx2 v145, v[152:153], s[42:43] offset:1024
	v_cvt_pk_bf16_f32 v154, v12, v13
	v_cvt_pk_bf16_f32 v155, v14, v15
	global_store_dwordx2 v145, v[154:155], s[42:43] offset:1536
	s_add_u32 s42, s42, 0x400000
	s_addc_u32 s43, s43, 0
	global_load_dwordx4 v[0:3], v144, s[24:25] offset:0
	global_load_dwordx4 v[4:7], v144, s[24:25] offset:1024
	global_load_dwordx4 v[8:11], v144, s[24:25] offset:2048
	global_load_dwordx4 v[12:15], v144, s[24:25] offset:3072
	s_add_u32 s24, s24, 0x800000
	s_addc_u32 s25, s25, 0
	s_waitcnt vmcnt(8)
; __device__ __forceinline__ unsigned pk2(float lo, float hi) { f32x2 v = {lo, hi}; bf16x2_t b = __builtin_convertvector(v, bf16x2_t); return __builtin_bit_cast(unsigned, b); }
; __device__ __forceinline__ float wave_sum(float v) { return wave_sum_fast(v); }
; __device__ __forceinline__ const float* xrow_ptr(const Ctx& p, int row) { return row < MPR ? p.in(0) + (size_t)row * DM : p.in(1) + (size_t)(row - MPR) * DM; }
; __device__ __forceinline__ void phase_prologue(const Ctx& p, LAS unsigned char* lds) {
;     ...
;         for (int m = gw; m < MP; m += NGW) {
;             const int mn = m + NGW;
;             if (mn < MR) {
; #pragma unroll
;                 for (int j = 0; j < 4; ++j) v2[j] = ((const f32x4*)xrow_ptr(p, mn))[lane + 64 * j]; }
;             u32x2* o8 = (u32x2*)(XN + (size_t)m * DM) + lane;
;             if (m < MR) {
;                 float sq = 0.f;
; #pragma unroll
;                 for (int j = 0; j < 4; ++j) sq += (v[j].x * v[j].x + v[j].y * v[j].y) + (v[j].z * v[j].z + v[j].w * v[j].w);
;                 const float rs = 1.f / sqrtf(wave_sum(sq) * (1.f / DM) + EPS);
; #pragma unroll
;                 for (int j = 0; j < 4; ++j) { u32x2 w; w.x = pk2(v[j].x * rs * g4[j].x, v[j].y * rs * g4[j].y); w.y = pk2(v[j].z * rs * g4[j].z, v[j].w * rs * g4[j].w); o8[64 * j] = w; }
;             } else {
; #pragma unroll
;                 for (int j = 0; j < 4; ++j) o8[64 * j] = (u32x2){0u, 0u}; }
; #pragma unroll
;             for (int j = 0; j < 4; ++j) v[j] = v2[j];
;         }
	v_mul_f32_e32 v96, v17, v17
	v_mul_f32_e32 v98, v19, v19
	v_fmac_f32_e32 v96, v16, v16
	v_fmac_f32_e32 v98, v18, v18
	v_add_f32_e32 v96, v96, v98
	v_mul_f32_e32 v97, v21, v21
	v_mul_f32_e32 v98, v23, v23
	v_fmac_f32_e32 v97, v20, v20
	v_fmac_f32_e32 v98, v22, v22
	v_add_f32_e32 v97, v97, v98
	v_add_f32_e32 v96, v97, v96
	v_mul_f32_e32 v97, v25, v25
	v_mul_f32_e32 v98, v27, v27
	v_fmac_f32_e32 v97, v24, v24
	v_fmac_f32_e32 v98, v26, v26
	v_add_f32_e32 v97, v97, v98
	v_add_f32_e32 v96, v97, v96
	v_mul_f32_e32 v97, v29, v29
	v_mul_f32_e32 v98, v31, v31
	v_fmac_f32_e32 v97, v28, v28
	v_fmac_f32_e32 v98, v30, v30
	v_add_f32_e32 v97, v97, v98
	v_add_f32_e32 v96, v97, v96
	s_nop 1
	v_add_f32_dpp v96, v96, v96 quad_perm:[1,0,3,2] row_mask:0xf bank_mask:0xf bound_ctrl:1
	s_nop 1
	v_add_f32_dpp v96, v96, v96 quad_perm:[2,3,0,1] row_mask:0xf bank_mask:0xf bound_ctrl:1
	s_nop 1
	v_add_f32_dpp v96, v96, v96 row_half_mirror row_mask:0xf bank_mask:0xf bound_ctrl:1
	s_nop 1
	v_add_f32_dpp v96, v96, v96 row_mirror row_mask:0xf bank_mask:0xf bound_ctrl:1
	v_mov_b32_e32 v97, v96
	s_nop 1
	v_permlane16_swap_b32_e32 v96, v97
	v_add_f32_e32 v96, v96, v97
	v_mov_b32_e32 v97, v96
	s_nop 1
	v_permlane32_swap_b32_e32 v96, v97
	v_add_f32_e32 v96, v96, v97
	v_fmamk_f32 v96, v96, 0x3a800000, v146
	v_mul_f32_e32 v97, 0x4f800000, v96
	v_cmp_gt_f32_e32 vcc, s33, v96
	s_nop 1
	v_cndmask_b32_e32 v96, v96, v97, vcc
	v_sqrt_f32_e32 v97, v96
	s_nop 0
	v_add_u32_e32 v98, -1, v97
	v_fma_f32 v99, -v98, v97, v96
	v_cmp_ge_f32_e64 s[4:5], 0, v99
	v_add_u32_e32 v99, 1, v97
	s_nop 0
	v_cndmask_b32_e64 v98, v97, v98, s[4:5]
	v_fma_f32 v97, -v99, v97, v96
	v_cmp_lt_f32_e64 s[4:5], 0, v97
	s_nop 1
	v_cndmask_b32_e64 v97, v98, v99, s[4:5]
	v_mul_f32_e32 v98, 0x37800000, v97
	v_cndmask_b32_e32 v97, v97, v98, vcc
	v_cmp_class_f32_e32 vcc, v96, v147
	s_nop 1
	v_cndmask_b32_e32 v96, v97, v96, vcc
	v_div_scale_f32 v97, s[4:5], v96, v96, 1.0
	v_rcp_f32_e32 v98, v97
	s_nop 0
	v_fma_f32 v99, -v97, v98, 1.0
	v_fmac_f32_e32 v98, v99, v98
	v_div_scale_f32 v99, vcc, 1.0, v96, 1.0
	v_mul_f32_e32 v100, v99, v98
	v_fma_f32 v101, -v97, v100, v99
	v_fmac_f32_e32 v100, v101, v98
	v_fma_f32 v97, -v97, v100, v99
	v_div_fmas_f32 v97, v97, v98, v100
	v_div_fixup_f32 v96, v97, v96, 1.0
	v_mul_f32_e32 v16, v16, v96
	v_mul_f32_e32 v17, v17, v96
	v_mul_f32_e32 v18, v18, v96
	v_mul_f32_e32 v19, v19, v96
	v_mul_f32_e32 v20, v20, v96
	v_mul_f32_e32 v21, v21, v96
	v_mul_f32_e32 v22, v22, v96
	v_mul_f32_e32 v23, v23, v96
	v_mul_f32_e32 v24, v24, v96
	v_mul_f32_e32 v25, v25, v96
	v_mul_f32_e32 v26, v26, v96
	v_mul_f32_e32 v27, v27, v96
	v_mul_f32_e32 v28, v28, v96
	v_mul_f32_e32 v29, v29, v96
	v_mul_f32_e32 v30, v30, v96
	v_mul_f32_e32 v31, v31, v96
	v_mul_f32_e32 v16, v128, v16
	v_mul_f32_e32 v17, v129, v17
	v_mul_f32_e32 v18, v130, v18
	v_mul_f32_e32 v19, v131, v19
	v_mul_f32_e32 v20, v132, v20
	v_mul_f32_e32 v21, v133, v21
	v_mul_f32_e32 v22, v134, v22
	v_mul_f32_e32 v23, v135, v23
	v_mul_f32_e32 v24, v136, v24
	v_mul_f32_e32 v25, v137, v25
	v_mul_f32_e32 v26, v138, v26
	v_mul_f32_e32 v27, v139, v27
	v_mul_f32_e32 v28, v140, v28
	v_mul_f32_e32 v29, v141, v29
	v_mul_f32_e32 v30, v142, v30
	v_mul_f32_e32 v31, v143, v31
	v_cvt_pk_bf16_f32 v148, v16, v17
	v_cvt_pk_bf16_f32 v149, v18, v19
	global_store_dwordx2 v145, v[148:149], s[42:43] offset:0
	v_cvt_pk_bf16_f32 v150, v20, v21
	v_cvt_pk_bf16_f32 v151, v22, v23
	global_store_dwordx2 v145, v[150:151], s[42:43] offset:512
	v_cvt_pk_bf16_f32 v152, v24, v25
	v_cvt_pk_bf16_f32 v153, v26, v27
	global_store_dwordx2 v145, v[152:153], s[42:43] offset:1024
	v_cvt_pk_bf16_f32 v154, v28, v29
	v_cvt_pk_bf16_f32 v155, v30, v31
	global_store_dwordx2 v145, v[154:155], s[42:43] offset:1536
	s_add_u32 s42, s42, 0x400000
	s_addc_u32 s43, s43, 0
	global_load_dwordx4 v[16:19], v144, s[24:25] offset:0
	global_load_dwordx4 v[20:23], v144, s[24:25] offset:1024
	global_load_dwordx4 v[24:27], v144, s[24:25] offset:2048
	global_load_dwordx4 v[28:31], v144, s[24:25] offset:3072
	s_add_u32 s24, s24, 0x800000
	s_addc_u32 s25, s25, 0
	s_mov_b32 s20, 2
.Lxn_loop:
	s_waitcnt vmcnt(8)
	v_mul_f32_e32 v96, v1, v1
	v_mul_f32_e32 v98, v3, v3
	v_fmac_f32_e32 v96, v0, v0
	v_fmac_f32_e32 v98, v2, v2
	v_add_f32_e32 v96, v96, v98
	v_mul_f32_e32 v97, v5, v5
	v_mul_f32_e32 v98, v7, v7
	v_fmac_f32_e32 v97, v4, v4
	v_fmac_f32_e32 v98, v6, v6
	v_add_f32_e32 v97, v97, v98
	v_add_f32_e32 v96, v97, v96
	v_mul_f32_e32 v97, v9, v9
	v_mul_f32_e32 v98, v11, v11
	v_fmac_f32_e32 v97, v8, v8
	v_fmac_f32_e32 v98, v10, v10
	v_add_f32_e32 v97, v97, v98
	v_add_f32_e32 v96, v97, v96
	v_mul_f32_e32 v97, v13, v13
	v_mul_f32_e32 v98, v15, v15
	v_fmac_f32_e32 v97, v12, v12
	v_fmac_f32_e32 v98, v14, v14
	v_add_f32_e32 v97, v97, v98
	v_add_f32_e32 v96, v97, v96
	s_nop 1
	v_add_f32_dpp v96, v96, v96 quad_perm:[1,0,3,2] row_mask:0xf bank_mask:0xf bound_ctrl:1
	s_nop 1
	v_add_f32_dpp v96, v96, v96 quad_perm:[2,3,0,1] row_mask:0xf bank_mask:0xf bound_ctrl:1
	s_nop 1
	v_add_f32_dpp v96, v96, v96 row_half_mirror row_mask:0xf bank_mask:0xf bound_ctrl:1
	s_nop 1
	v_add_f32_dpp v96, v96, v96 row_mirror row_mask:0xf bank_mask:0xf bound_ctrl:1
	v_mov_b32_e32 v97, v96
	s_nop 1
	v_permlane16_swap_b32_e32 v96, v97
	v_add_f32_e32 v96, v96, v97
	v_mov_b32_e32 v97, v96
	s_nop 1
	v_permlane32_swap_b32_e32 v96, v97
	v_add_f32_e32 v96, v96, v97
	v_fmamk_f32 v96, v96, 0x3a800000, v146
	v_mul_f32_e32 v97, 0x4f800000, v96
	v_cmp_gt_f32_e32 vcc, s33, v96
	s_nop 1
	v_cndmask_b32_e32 v96, v96, v97, vcc
	v_sqrt_f32_e32 v97, v96
	s_nop 0
	v_add_u32_e32 v98, -1, v97
	v_fma_f32 v99, -v98, v97, v96
	v_cmp_ge_f32_e64 s[4:5], 0, v99
	v_add_u32_e32 v99, 1, v97
; __device__ __forceinline__ unsigned pk2(float lo, float hi) { f32x2 v = {lo, hi}; bf16x2_t b = __builtin_convertvector(v, bf16x2_t); return __builtin_bit_cast(unsigned, b); }
; __device__ __forceinline__ float wave_sum(float v) { return wave_sum_fast(v); }
; __device__ __forceinline__ const float* xrow_ptr(const Ctx& p, int row) { return row < MPR ? p.in(0) + (size_t)row * DM : p.in(1) + (size_t)(row - MPR) * DM; }
; __device__ __forceinline__ void phase_prologue(const Ctx& p, LAS unsigned char* lds) {
;     ...
;         for (int m = gw; m < MP; m += NGW) {
;             const int mn = m + NGW;
;             if (mn < MR) {
; #pragma unroll
;                 for (int j = 0; j < 4; ++j) v2[j] = ((const f32x4*)xrow_ptr(p, mn))[lane + 64 * j]; }
;             u32x2* o8 = (u32x2*)(XN + (size_t)m * DM) + lane;
;             if (m < MR) {
;                 float sq = 0.f;
; #pragma unroll
;                 for (int j = 0; j < 4; ++j) sq += (v[j].x * v[j].x + v[j].y * v[j].y) + (v[j].z * v[j].z + v[j].w * v[j].w);
;                 const float rs = 1.f / sqrtf(wave_sum(sq) * (1.f / DM) + EPS);
; #pragma unroll
;                 for (int j = 0; j < 4; ++j) { u32x2 w; w.x = pk2(v[j].x * rs * g4[j].x, v[j].y * rs * g4[j].y); w.y = pk2(v[j].z * rs * g4[j].z, v[j].w * rs * g4[j].w); o8[64 * j] = w; }
;             } else {
; #pragma unroll
;                 for (int j = 0; j < 4; ++j) o8[64 * j] = (u32x2){0u, 0u}; }
; #pragma unroll
;             for (int j = 0; j < 4; ++j) v[j] = v2[j];
;         }
	s_nop 0
	v_cndmask_b32_e64 v98, v97, v98, s[4:5]
	v_fma_f32 v97, -v99, v97, v96
	v_cmp_lt_f32_e64 s[4:5], 0, v97
	s_nop 1
	v_cndmask_b32_e64 v97, v98, v99, s[4:5]
	v_mul_f32_e32 v98, 0x37800000, v97
	v_cndmask_b32_e32 v97, v97, v98, vcc
	v_cmp_class_f32_e32 vcc, v96, v147
	s_nop 1
	v_cndmask_b32_e32 v96, v97, v96, vcc
	v_div_scale_f32 v97, s[4:5], v96, v96, 1.0
	v_rcp_f32_e32 v98, v97
	s_nop 0
	v_fma_f32 v99, -v97, v98, 1.0
	v_fmac_f32_e32 v98, v99, v98
	v_div_scale_f32 v99, vcc, 1.0, v96, 1.0
	v_mul_f32_e32 v100, v99, v98
	v_fma_f32 v101, -v97, v100, v99
	v_fmac_f32_e32 v100, v101, v98
	v_fma_f32 v97, -v97, v100, v99
	v_div_fmas_f32 v97, v97, v98, v100
	v_div_fixup_f32 v96, v97, v96, 1.0
	v_mul_f32_e32 v0, v0, v96
	v_mul_f32_e32 v1, v1, v96
	v_mul_f32_e32 v2, v2, v96
	v_mul_f32_e32 v3, v3, v96
	v_mul_f32_e32 v4, v4, v96
	v_mul_f32_e32 v5, v5, v96
	v_mul_f32_e32 v6, v6, v96
	v_mul_f32_e32 v7, v7, v96
	v_mul_f32_e32 v8, v8, v96
	v_mul_f32_e32 v9, v9, v96
	v_mul_f32_e32 v10, v10, v96
	v_mul_f32_e32 v11, v11, v96
	v_mul_f32_e32 v12, v12, v96
	v_mul_f32_e32 v13, v13, v96
	v_mul_f32_e32 v14, v14, v96
	v_mul_f32_e32 v15, v15, v96
	v_mul_f32_e32 v0, v128, v0
	v_mul_f32_e32 v1, v129, v1
	v_mul_f32_e32 v2, v130, v2
	v_mul_f32_e32 v3, v131, v3
	v_mul_f32_e32 v4, v132, v4
	v_mul_f32_e32 v5, v133, v5
	v_mul_f32_e32 v6, v134, v6
	v_mul_f32_e32 v7, v135, v7
	v_mul_f32_e32 v8, v136, v8
	v_mul_f32_e32 v9, v137, v9
	v_mul_f32_e32 v10, v138, v10
	v_mul_f32_e32 v11, v139, v11
	v_mul_f32_e32 v12, v140, v12
	v_mul_f32_e32 v13, v141, v13
	v_mul_f32_e32 v14, v142, v14
	v_mul_f32_e32 v15, v143, v15
	v_cvt_pk_bf16_f32 v148, v0, v1
	v_cvt_pk_bf16_f32 v149, v2, v3
	global_store_dwordx2 v145, v[148:149], s[42:43] offset:0
	v_cvt_pk_bf16_f32 v150, v4, v5
	v_cvt_pk_bf16_f32 v151, v6, v7
	global_store_dwordx2 v145, v[150:151], s[42:43] offset:512
	v_cvt_pk_bf16_f32 v152, v8, v9
	v_cvt_pk_bf16_f32 v153, v10, v11
	global_store_dwordx2 v145, v[152:153], s[42:43] offset:1024
	v_cvt_pk_bf16_f32 v154, v12, v13
	v_cvt_pk_bf16_f32 v155, v14, v15
	global_store_dwordx2 v145, v[154:155], s[42:43] offset:1536
	s_add_u32 s42, s42, 0x400000
	s_addc_u32 s43, s43, 0
	global_load_dwordx4 v[0:3], v144, s[24:25] offset:0
	global_load_dwordx4 v[4:7], v144, s[24:25] offset:1024
	global_load_dwordx4 v[8:11], v144, s[24:25] offset:2048
	global_load_dwordx4 v[12:15], v144, s[24:25] offset:3072
	s_add_u32 s24, s24, 0x800000
	s_addc_u32 s25, s25, 0
	s_waitcnt vmcnt(8)
	v_mul_f32_e32 v96, v17, v17
	v_mul_f32_e32 v98, v19, v19
	v_fmac_f32_e32 v96, v16, v16
	v_fmac_f32_e32 v98, v18, v18
	v_add_f32_e32 v96, v96, v98
	v_mul_f32_e32 v97, v21, v21
	v_mul_f32_e32 v98, v23, v23
	v_fmac_f32_e32 v97, v20, v20
	v_fmac_f32_e32 v98, v22, v22
	v_add_f32_e32 v97, v97, v98
	v_add_f32_e32 v96, v97, v96
	v_mul_f32_e32 v97, v25, v25
	v_mul_f32_e32 v98, v27, v27
	v_fmac_f32_e32 v97, v24, v24
	v_fmac_f32_e32 v98, v26, v26
	v_add_f32_e32 v97, v97, v98
	v_add_f32_e32 v96, v97, v96
	v_mul_f32_e32 v97, v29, v29
	v_mul_f32_e32 v98, v31, v31
	v_fmac_f32_e32 v97, v28, v28
	v_fmac_f32_e32 v98, v30, v30
	v_add_f32_e32 v97, v97, v98
	v_add_f32_e32 v96, v97, v96
	s_nop 1
	v_add_f32_dpp v96, v96, v96 quad_perm:[1,0,3,2] row_mask:0xf bank_mask:0xf bound_ctrl:1
	s_nop 1
	v_add_f32_dpp v96, v96, v96 quad_perm:[2,3,0,1] row_mask:0xf bank_mask:0xf bound_ctrl:1
	s_nop 1
	v_add_f32_dpp v96, v96, v96 row_half_mirror row_mask:0xf bank_mask:0xf bound_ctrl:1
	s_nop 1
	v_add_f32_dpp v96, v96, v96 row_mirror row_mask:0xf bank_mask:0xf bound_ctrl:1
	v_mov_b32_e32 v97, v96
	s_nop 1
	v_permlane16_swap_b32_e32 v96, v97
	v_add_f32_e32 v96, v96, v97
	v_mov_b32_e32 v97, v96
	s_nop 1
	v_permlane32_swap_b32_e32 v96, v97
	v_add_f32_e32 v96, v96, v97
	v_fmamk_f32 v96, v96, 0x3a800000, v146
	v_mul_f32_e32 v97, 0x4f800000, v96
	v_cmp_gt_f32_e32 vcc, s33, v96
	s_nop 1
	v_cndmask_b32_e32 v96, v96, v97, vcc
	v_sqrt_f32_e32 v97, v96
	s_nop 0
	v_add_u32_e32 v98, -1, v97
	v_fma_f32 v99, -v98, v97, v96
	v_cmp_ge_f32_e64 s[4:5], 0, v99
	v_add_u32_e32 v99, 1, v97
	s_nop 0
	v_cndmask_b32_e64 v98, v97, v98, s[4:5]
	v_fma_f32 v97, -v99, v97, v96
	v_cmp_lt_f32_e64 s[4:5], 0, v97
	s_nop 1
	v_cndmask_b32_e64 v97, v98, v99, s[4:5]
	v_mul_f32_e32 v98, 0x37800000, v97
	v_cndmask_b32_e32 v97, v97, v98, vcc
	v_cmp_class_f32_e32 vcc, v96, v147
	s_nop 1
	v_cndmask_b32_e32 v96, v97, v96, vcc
	v_div_scale_f32 v97, s[4:5], v96, v96, 1.0
	v_rcp_f32_e32 v98, v97
	s_nop 0
	v_fma_f32 v99, -v97, v98, 1.0
	v_fmac_f32_e32 v98, v99, v98
	v_div_scale_f32 v99, vcc, 1.0, v96, 1.0
	v_mul_f32_e32 v100, v99, v98
	v_fma_f32 v101, -v97, v100, v99
	v_fmac_f32_e32 v100, v101, v98
	v_fma_f32 v97, -v97, v100, v99
	v_div_fmas_f32 v97, v97, v98, v100
	v_div_fixup_f32 v96, v97, v96, 1.0
	v_mul_f32_e32 v16, v16, v96
	v_mul_f32_e32 v17, v17, v96
	v_mul_f32_e32 v18, v18, v96
	v_mul_f32_e32 v19, v19, v96
	v_mul_f32_e32 v20, v20, v96
	v_mul_f32_e32 v21, v21, v96
	v_mul_f32_e32 v22, v22, v96
	v_mul_f32_e32 v23, v23, v96
	v_mul_f32_e32 v24, v24, v96
	v_mul_f32_e32 v25, v25, v96
	v_mul_f32_e32 v26, v26, v96
	v_mul_f32_e32 v27, v27, v96
	v_mul_f32_e32 v28, v28, v96
	v_mul_f32_e32 v29, v29, v96
	v_mul_f32_e32 v30, v30, v96
	v_mul_f32_e32 v31, v31, v96
	v_mul_f32_e32 v16, v128, v16
	v_mul_f32_e32 v17, v129, v17
	v_mul_f32_e32 v18, v130, v18
	v_mul_f32_e32 v19, v131, v19
	v_mul_f32_e32 v20, v132, v20
	v_mul_f32_e32 v21, v133, v21
	v_mul_f32_e32 v22, v134, v22
	v_mul_f32_e32 v23, v135, v23
	v_mul_f32_e32 v24, v136, v24
	v_mul_f32_e32 v25, v137, v25
	v_mul_f32_e32 v26, v138, v26
	v_mul_f32_e32 v27, v139, v27
	v_mul_f32_e32 v28, v140, v28
	v_mul_f32_e32 v29, v141, v29
	v_mul_f32_e32 v30, v142, v30
	v_mul_f32_e32 v31, v143, v31
	v_cvt_pk_bf16_f32 v148, v16, v17
	v_cvt_pk_bf16_f32 v149, v18, v19
	global_store_dwordx2 v145, v[148:149], s[42:43] offset:0
	v_cvt_pk_bf16_f32 v150, v20, v21
	v_cvt_pk_bf16_f32 v151, v22, v23
	global_store_dwordx2 v145, v[150:151], s[42:43] offset:512
	v_cvt_pk_bf16_f32 v152, v24, v25
	v_cvt_pk_bf16_f32 v153, v26, v27
	global_store_dwordx2 v145, v[152:153], s[42:43] offset:1024
	v_cvt_pk_bf16_f32 v154, v28, v29
	v_cvt_pk_bf16_f32 v155, v30, v31
	global_store_dwordx2 v145, v[154:155], s[42:43] offset:1536
	s_add_u32 s42, s42, 0x400000
	s_addc_u32 s43, s43, 0
	global_load_dwordx4 v[16:19], v144, s[24:25] offset:0
	global_load_dwordx4 v[20:23], v144, s[24:25] offset:1024
	global_load_dwordx4 v[24:27], v144, s[24:25] offset:2048
	global_load_dwordx4 v[28:31], v144, s[24:25] offset:3072
	s_add_u32 s24, s24, 0x800000
	s_addc_u32 s25, s25, 0
	s_sub_u32 s20, s20, 1
	s_cmp_lg_u32 s20, 0
	s_cbranch_scc1 .Lxn_loop
; __device__ __forceinline__ unsigned pk2(float lo, float hi) { f32x2 v = {lo, hi}; bf16x2_t b = __builtin_convertvector(v, bf16x2_t); return __builtin_bit_cast(unsigned, b); }
; __device__ __forceinline__ float wave_sum(float v) { return wave_sum_fast(v); }
; __device__ __forceinline__ const float* xrow_ptr(const Ctx& p, int row) { return row < MPR ? p.in(0) + (size_t)row * DM : p.in(1) + (size_t)(row - MPR) * DM; }
; __device__ __forceinline__ void phase_prologue(const Ctx& p, LAS unsigned char* lds) {
;     ...
;         for (int m = gw; m < MP; m += NGW) {
;             const int mn = m + NGW;
;             if (mn < MR) {
; #pragma unroll
;                 for (int j = 0; j < 4; ++j) v2[j] = ((const f32x4*)xrow_ptr(p, mn))[lane + 64 * j]; }
;             u32x2* o8 = (u32x2*)(XN + (size_t)m * DM) + lane;
;             if (m < MR) {
;                 float sq = 0.f;
; #pragma unroll
;                 for (int j = 0; j < 4; ++j) sq += (v[j].x * v[j].x + v[j].y * v[j].y) + (v[j].z * v[j].z + v[j].w * v[j].w);
;                 const float rs = 1.f / sqrtf(wave_sum(sq) * (1.f / DM) + EPS);
; #pragma unroll
;                 for (int j = 0; j < 4; ++j) { u32x2 w; w.x = pk2(v[j].x * rs * g4[j].x, v[j].y * rs * g4[j].y); w.y = pk2(v[j].z * rs * g4[j].z, v[j].w * rs * g4[j].w); o8[64 * j] = w; }
;             } else {
; #pragma unroll
;                 for (int j = 0; j < 4; ++j) o8[64 * j] = (u32x2){0u, 0u}; }
; #pragma unroll
;             for (int j = 0; j < 4; ++j) v[j] = v2[j];
;         }
	s_waitcnt vmcnt(8)
	v_mul_f32_e32 v96, v1, v1
	v_mul_f32_e32 v98, v3, v3
	v_fmac_f32_e32 v96, v0, v0
	v_fmac_f32_e32 v98, v2, v2
	v_add_f32_e32 v96, v96, v98
	v_mul_f32_e32 v97, v5, v5
	v_mul_f32_e32 v98, v7, v7
	v_fmac_f32_e32 v97, v4, v4
	v_fmac_f32_e32 v98, v6, v6
	v_add_f32_e32 v97, v97, v98
	v_add_f32_e32 v96, v97, v96
	v_mul_f32_e32 v97, v9, v9
	v_mul_f32_e32 v98, v11, v11
	v_fmac_f32_e32 v97, v8, v8
	v_fmac_f32_e32 v98, v10, v10
	v_add_f32_e32 v97, v97, v98
	v_add_f32_e32 v96, v97, v96
	v_mul_f32_e32 v97, v13, v13
	v_mul_f32_e32 v98, v15, v15
	v_fmac_f32_e32 v97, v12, v12
	v_fmac_f32_e32 v98, v14, v14
	v_add_f32_e32 v97, v97, v98
	v_add_f32_e32 v96, v97, v96
	s_nop 1
	v_add_f32_dpp v96, v96, v96 quad_perm:[1,0,3,2] row_mask:0xf bank_mask:0xf bound_ctrl:1
	s_nop 1
	v_add_f32_dpp v96, v96, v96 quad_perm:[2,3,0,1] row_mask:0xf bank_mask:0xf bound_ctrl:1
	s_nop 1
	v_add_f32_dpp v96, v96, v96 row_half_mirror row_mask:0xf bank_mask:0xf bound_ctrl:1
	s_nop 1
	v_add_f32_dpp v96, v96, v96 row_mirror row_mask:0xf bank_mask:0xf bound_ctrl:1
	v_mov_b32_e32 v97, v96
	s_nop 1
	v_permlane16_swap_b32_e32 v96, v97
	v_add_f32_e32 v96, v96, v97
	v_mov_b32_e32 v97, v96
	s_nop 1
	v_permlane32_swap_b32_e32 v96, v97
	v_add_f32_e32 v96, v96, v97
	v_fmamk_f32 v96, v96, 0x3a800000, v146
	v_mul_f32_e32 v97, 0x4f800000, v96
	v_cmp_gt_f32_e32 vcc, s33, v96
	s_nop 1
	v_cndmask_b32_e32 v96, v96, v97, vcc
	v_sqrt_f32_e32 v97, v96
	s_nop 0
	v_add_u32_e32 v98, -1, v97
	v_fma_f32 v99, -v98, v97, v96
	v_cmp_ge_f32_e64 s[4:5], 0, v99
	v_add_u32_e32 v99, 1, v97
	s_nop 0
	v_cndmask_b32_e64 v98, v97, v98, s[4:5]
	v_fma_f32 v97, -v99, v97, v96
	v_cmp_lt_f32_e64 s[4:5], 0, v97
	s_nop 1
	v_cndmask_b32_e64 v97, v98, v99, s[4:5]
	v_mul_f32_e32 v98, 0x37800000, v97
	v_cndmask_b32_e32 v97, v97, v98, vcc
	v_cmp_class_f32_e32 vcc, v96, v147
	s_nop 1
	v_cndmask_b32_e32 v96, v97, v96, vcc
	v_div_scale_f32 v97, s[4:5], v96, v96, 1.0
	v_rcp_f32_e32 v98, v97
	s_nop 0
	v_fma_f32 v99, -v97, v98, 1.0
	v_fmac_f32_e32 v98, v99, v98
	v_div_scale_f32 v99, vcc, 1.0, v96, 1.0
	v_mul_f32_e32 v100, v99, v98
	v_fma_f32 v101, -v97, v100, v99
	v_fmac_f32_e32 v100, v101, v98
	v_fma_f32 v97, -v97, v100, v99
	v_div_fmas_f32 v97, v97, v98, v100
	v_div_fixup_f32 v96, v97, v96, 1.0
	v_mul_f32_e32 v0, v0, v96
	v_mul_f32_e32 v1, v1, v96
	v_mul_f32_e32 v2, v2, v96
	v_mul_f32_e32 v3, v3, v96
	v_mul_f32_e32 v4, v4, v96
	v_mul_f32_e32 v5, v5, v96
	v_mul_f32_e32 v6, v6, v96
	v_mul_f32_e32 v7, v7, v96
	v_mul_f32_e32 v8, v8, v96
	v_mul_f32_e32 v9, v9, v96
	v_mul_f32_e32 v10, v10, v96
	v_mul_f32_e32 v11, v11, v96
	v_mul_f32_e32 v12, v12, v96
	v_mul_f32_e32 v13, v13, v96
	v_mul_f32_e32 v14, v14, v96
	v_mul_f32_e32 v15, v15, v96
	v_mul_f32_e32 v0, v128, v0
	v_mul_f32_e32 v1, v129, v1
	v_mul_f32_e32 v2, v130, v2
	v_mul_f32_e32 v3, v131, v3
	v_mul_f32_e32 v4, v132, v4
	v_mul_f32_e32 v5, v133, v5
	v_mul_f32_e32 v6, v134, v6
	v_mul_f32_e32 v7, v135, v7
	v_mul_f32_e32 v8, v136, v8
	v_mul_f32_e32 v9, v137, v9
	v_mul_f32_e32 v10, v138, v10
	v_mul_f32_e32 v11, v139, v11
	v_mul_f32_e32 v12, v140, v12
	v_mul_f32_e32 v13, v141, v13
	v_mul_f32_e32 v14, v142, v14
	v_mul_f32_e32 v15, v143, v15
	v_cvt_pk_bf16_f32 v148, v0, v1
	v_cvt_pk_bf16_f32 v149, v2, v3
	global_store_dwordx2 v145, v[148:149], s[42:43] offset:0
	v_cvt_pk_bf16_f32 v150, v4, v5
	v_cvt_pk_bf16_f32 v151, v6, v7
	global_store_dwordx2 v145, v[150:151], s[42:43] offset:512
	v_cvt_pk_bf16_f32 v152, v8, v9
	v_cvt_pk_bf16_f32 v153, v10, v11
	global_store_dwordx2 v145, v[152:153], s[42:43] offset:1024
	v_cvt_pk_bf16_f32 v154, v12, v13
	v_cvt_pk_bf16_f32 v155, v14, v15
	global_store_dwordx2 v145, v[154:155], s[42:43] offset:1536
	s_add_u32 s42, s42, 0x400000
	s_addc_u32 s43, s43, 0
	s_waitcnt vmcnt(4)
	v_mul_f32_e32 v96, v17, v17
	v_mul_f32_e32 v98, v19, v19
	v_fmac_f32_e32 v96, v16, v16
	v_fmac_f32_e32 v98, v18, v18
	v_add_f32_e32 v96, v96, v98
	v_mul_f32_e32 v97, v21, v21
	v_mul_f32_e32 v98, v23, v23
	v_fmac_f32_e32 v97, v20, v20
	v_fmac_f32_e32 v98, v22, v22
	v_add_f32_e32 v97, v97, v98
	v_add_f32_e32 v96, v97, v96
	v_mul_f32_e32 v97, v25, v25
	v_mul_f32_e32 v98, v27, v27
	v_fmac_f32_e32 v97, v24, v24
	v_fmac_f32_e32 v98, v26, v26
	v_add_f32_e32 v97, v97, v98
	v_add_f32_e32 v96, v97, v96
	v_mul_f32_e32 v97, v29, v29
	v_mul_f32_e32 v98, v31, v31
	v_fmac_f32_e32 v97, v28, v28
	v_fmac_f32_e32 v98, v30, v30
	v_add_f32_e32 v97, v97, v98
	v_add_f32_e32 v96, v97, v96
	s_nop 1
	v_add_f32_dpp v96, v96, v96 quad_perm:[1,0,3,2] row_mask:0xf bank_mask:0xf bound_ctrl:1
	s_nop 1
	v_add_f32_dpp v96, v96, v96 quad_perm:[2,3,0,1] row_mask:0xf bank_mask:0xf bound_ctrl:1
	s_nop 1
	v_add_f32_dpp v96, v96, v96 row_half_mirror row_mask:0xf bank_mask:0xf bound_ctrl:1
	s_nop 1
	v_add_f32_dpp v96, v96, v96 row_mirror row_mask:0xf bank_mask:0xf bound_ctrl:1
	v_mov_b32_e32 v97, v96
	s_nop 1
	v_permlane16_swap_b32_e32 v96, v97
	v_add_f32_e32 v96, v96, v97
	v_mov_b32_e32 v97, v96
	s_nop 1
	v_permlane32_swap_b32_e32 v96, v97
	v_add_f32_e32 v96, v96, v97
	v_fmamk_f32 v96, v96, 0x3a800000, v146
	v_mul_f32_e32 v97, 0x4f800000, v96
	v_cmp_gt_f32_e32 vcc, s33, v96
	s_nop 1
	v_cndmask_b32_e32 v96, v96, v97, vcc
	v_sqrt_f32_e32 v97, v96
	s_nop 0
	v_add_u32_e32 v98, -1, v97
	v_fma_f32 v99, -v98, v97, v96
	v_cmp_ge_f32_e64 s[4:5], 0, v99
	v_add_u32_e32 v99, 1, v97
	s_nop 0
	v_cndmask_b32_e64 v98, v97, v98, s[4:5]
	v_fma_f32 v97, -v99, v97, v96
	v_cmp_lt_f32_e64 s[4:5], 0, v97
	s_nop 1
	v_cndmask_b32_e64 v97, v98, v99, s[4:5]
	v_mul_f32_e32 v98, 0x37800000, v97
	v_cndmask_b32_e32 v97, v97, v98, vcc
	v_cmp_class_f32_e32 vcc, v96, v147
	s_nop 1
	v_cndmask_b32_e32 v96, v97, v96, vcc
	v_div_scale_f32 v97, s[4:5], v96, v96, 1.0
; __device__ __forceinline__ unsigned pk2(float lo, float hi) { f32x2 v = {lo, hi}; bf16x2_t b = __builtin_convertvector(v, bf16x2_t); return __builtin_bit_cast(unsigned, b); }
; __device__ __forceinline__ float wave_sum(float v) { return wave_sum_fast(v); }
;     __device__ __forceinline__ const float* in(int i) const { return (const float*)ptr(i); }
; __device__ __forceinline__ const float* xrow_ptr(const Ctx& p, int row) { return row < MPR ? p.in(0) + (size_t)row * DM : p.in(1) + (size_t)(row - MPR) * DM; }
; __device__ __forceinline__ void phase_prologue(const Ctx& p, LAS unsigned char* lds) {
;     ...
;         for (int m = gw; m < MP; m += NGW) {
;             const int mn = m + NGW;
;             if (mn < MR) {
; #pragma unroll
;                 for (int j = 0; j < 4; ++j) v2[j] = ((const f32x4*)xrow_ptr(p, mn))[lane + 64 * j]; }
;             u32x2* o8 = (u32x2*)(XN + (size_t)m * DM) + lane;
;             if (m < MR) {
;                 float sq = 0.f;
; #pragma unroll
;                 for (int j = 0; j < 4; ++j) sq += (v[j].x * v[j].x + v[j].y * v[j].y) + (v[j].z * v[j].z + v[j].w * v[j].w);
;                 const float rs = 1.f / sqrtf(wave_sum(sq) * (1.f / DM) + EPS);
; #pragma unroll
;                 for (int j = 0; j < 4; ++j) { u32x2 w; w.x = pk2(v[j].x * rs * g4[j].x, v[j].y * rs * g4[j].y); w.y = pk2(v[j].z * rs * g4[j].z, v[j].w * rs * g4[j].w); o8[64 * j] = w; }
;             } else {
; #pragma unroll
;                 for (int j = 0; j < 4; ++j) o8[64 * j] = (u32x2){0u, 0u}; }
	v_rcp_f32_e32 v98, v97
	s_nop 0
	v_fma_f32 v99, -v97, v98, 1.0
	v_fmac_f32_e32 v98, v99, v98
	v_div_scale_f32 v99, vcc, 1.0, v96, 1.0
	v_mul_f32_e32 v100, v99, v98
	v_fma_f32 v101, -v97, v100, v99
	v_fmac_f32_e32 v100, v101, v98
	v_fma_f32 v97, -v97, v100, v99
	v_div_fmas_f32 v97, v97, v98, v100
	v_div_fixup_f32 v96, v97, v96, 1.0
	v_mul_f32_e32 v16, v16, v96
	v_mul_f32_e32 v17, v17, v96
	v_mul_f32_e32 v18, v18, v96
	v_mul_f32_e32 v19, v19, v96
	v_mul_f32_e32 v20, v20, v96
	v_mul_f32_e32 v21, v21, v96
	v_mul_f32_e32 v22, v22, v96
	v_mul_f32_e32 v23, v23, v96
	v_mul_f32_e32 v24, v24, v96
	v_mul_f32_e32 v25, v25, v96
	v_mul_f32_e32 v26, v26, v96
	v_mul_f32_e32 v27, v27, v96
	v_mul_f32_e32 v28, v28, v96
	v_mul_f32_e32 v29, v29, v96
	v_mul_f32_e32 v30, v30, v96
	v_mul_f32_e32 v31, v31, v96
	v_mul_f32_e32 v16, v128, v16
	v_mul_f32_e32 v17, v129, v17
	v_mul_f32_e32 v18, v130, v18
	v_mul_f32_e32 v19, v131, v19
	v_mul_f32_e32 v20, v132, v20
	v_mul_f32_e32 v21, v133, v21
	v_mul_f32_e32 v22, v134, v22
	v_mul_f32_e32 v23, v135, v23
	v_mul_f32_e32 v24, v136, v24
	v_mul_f32_e32 v25, v137, v25
	v_mul_f32_e32 v26, v138, v26
	v_mul_f32_e32 v27, v139, v27
	v_mul_f32_e32 v28, v140, v28
	v_mul_f32_e32 v29, v141, v29
	v_mul_f32_e32 v30, v142, v30
	v_mul_f32_e32 v31, v143, v31
	v_cvt_pk_bf16_f32 v148, v16, v17
	v_cvt_pk_bf16_f32 v149, v18, v19
	global_store_dwordx2 v145, v[148:149], s[42:43] offset:0
	v_cvt_pk_bf16_f32 v150, v20, v21
	v_cvt_pk_bf16_f32 v151, v22, v23
	global_store_dwordx2 v145, v[150:151], s[42:43] offset:512
	v_cvt_pk_bf16_f32 v152, v24, v25
	v_cvt_pk_bf16_f32 v153, v26, v27
	global_store_dwordx2 v145, v[152:153], s[42:43] offset:1024
	v_cvt_pk_bf16_f32 v154, v28, v29
	v_cvt_pk_bf16_f32 v155, v30, v31
	global_store_dwordx2 v145, v[154:155], s[42:43] offset:1536
	s_add_u32 s42, s42, 0x400000
	s_addc_u32 s43, s43, 0
	s_cmpk_lt_u32 s10, 0x100
	s_cbranch_scc0 .Lxn_done
	s_cmpk_lt_u32 s10, 0x80
	s_cbranch_scc0 .Lxn_zero
	s_lshl_b32 s2, s10, 12
	s_add_u32 s24, s16, s2
	s_addc_u32 s25, s17, 0
	s_waitcnt vmcnt(0)
	global_load_dwordx4 v[0:3], v144, s[24:25] offset:0
	global_load_dwordx4 v[4:7], v144, s[24:25] offset:1024
	global_load_dwordx4 v[8:11], v144, s[24:25] offset:2048
	global_load_dwordx4 v[12:15], v144, s[24:25] offset:3072
	s_waitcnt vmcnt(0)
	v_mul_f32_e32 v96, v1, v1
	v_mul_f32_e32 v98, v3, v3
	v_fmac_f32_e32 v96, v0, v0
	v_fmac_f32_e32 v98, v2, v2
	v_add_f32_e32 v96, v96, v98
	v_mul_f32_e32 v97, v5, v5
	v_mul_f32_e32 v98, v7, v7
	v_fmac_f32_e32 v97, v4, v4
	v_fmac_f32_e32 v98, v6, v6
	v_add_f32_e32 v97, v97, v98
	v_add_f32_e32 v96, v97, v96
	v_mul_f32_e32 v97, v9, v9
	v_mul_f32_e32 v98, v11, v11
	v_fmac_f32_e32 v97, v8, v8
	v_fmac_f32_e32 v98, v10, v10
	v_add_f32_e32 v97, v97, v98
	v_add_f32_e32 v96, v97, v96
	v_mul_f32_e32 v97, v13, v13
	v_mul_f32_e32 v98, v15, v15
	v_fmac_f32_e32 v97, v12, v12
	v_fmac_f32_e32 v98, v14, v14
	v_add_f32_e32 v97, v97, v98
	v_add_f32_e32 v96, v97, v96
	s_nop 1
	v_add_f32_dpp v96, v96, v96 quad_perm:[1,0,3,2] row_mask:0xf bank_mask:0xf bound_ctrl:1
	s_nop 1
	v_add_f32_dpp v96, v96, v96 quad_perm:[2,3,0,1] row_mask:0xf bank_mask:0xf bound_ctrl:1
	s_nop 1
	v_add_f32_dpp v96, v96, v96 row_half_mirror row_mask:0xf bank_mask:0xf bound_ctrl:1
	s_nop 1
	v_add_f32_dpp v96, v96, v96 row_mirror row_mask:0xf bank_mask:0xf bound_ctrl:1
	v_mov_b32_e32 v97, v96
	s_nop 1
	v_permlane16_swap_b32_e32 v96, v97
	v_add_f32_e32 v96, v96, v97
	v_mov_b32_e32 v97, v96
	s_nop 1
	v_permlane32_swap_b32_e32 v96, v97
	v_add_f32_e32 v96, v96, v97
	v_fmamk_f32 v96, v96, 0x3a800000, v146
	v_mul_f32_e32 v97, 0x4f800000, v96
	v_cmp_gt_f32_e32 vcc, s33, v96
	s_nop 1
	v_cndmask_b32_e32 v96, v96, v97, vcc
	v_sqrt_f32_e32 v97, v96
	s_nop 0
	v_add_u32_e32 v98, -1, v97
	v_fma_f32 v99, -v98, v97, v96
	v_cmp_ge_f32_e64 s[4:5], 0, v99
	v_add_u32_e32 v99, 1, v97
	s_nop 0
	v_cndmask_b32_e64 v98, v97, v98, s[4:5]
	v_fma_f32 v97, -v99, v97, v96
	v_cmp_lt_f32_e64 s[4:5], 0, v97
	s_nop 1
	v_cndmask_b32_e64 v97, v98, v99, s[4:5]
	v_mul_f32_e32 v98, 0x37800000, v97
	v_cndmask_b32_e32 v97, v97, v98, vcc
	v_cmp_class_f32_e32 vcc, v96, v147
	s_nop 1
	v_cndmask_b32_e32 v96, v97, v96, vcc
	v_div_scale_f32 v97, s[4:5], v96, v96, 1.0
	v_rcp_f32_e32 v98, v97
	s_nop 0
	v_fma_f32 v99, -v97, v98, 1.0
	v_fmac_f32_e32 v98, v99, v98
	v_div_scale_f32 v99, vcc, 1.0, v96, 1.0
	v_mul_f32_e32 v100, v99, v98
	v_fma_f32 v101, -v97, v100, v99
	v_fmac_f32_e32 v100, v101, v98
	v_fma_f32 v97, -v97, v100, v99
	v_div_fmas_f32 v97, v97, v98, v100
	v_div_fixup_f32 v96, v97, v96, 1.0
	v_mul_f32_e32 v0, v0, v96
	v_mul_f32_e32 v1, v1, v96
	v_mul_f32_e32 v2, v2, v96
	v_mul_f32_e32 v3, v3, v96
	v_mul_f32_e32 v4, v4, v96
	v_mul_f32_e32 v5, v5, v96
	v_mul_f32_e32 v6, v6, v96
	v_mul_f32_e32 v7, v7, v96
	v_mul_f32_e32 v8, v8, v96
	v_mul_f32_e32 v9, v9, v96
	v_mul_f32_e32 v10, v10, v96
	v_mul_f32_e32 v11, v11, v96
	v_mul_f32_e32 v12, v12, v96
	v_mul_f32_e32 v13, v13, v96
	v_mul_f32_e32 v14, v14, v96
	v_mul_f32_e32 v15, v15, v96
	v_mul_f32_e32 v0, v128, v0
	v_mul_f32_e32 v1, v129, v1
	v_mul_f32_e32 v2, v130, v2
	v_mul_f32_e32 v3, v131, v3
	v_mul_f32_e32 v4, v132, v4
	v_mul_f32_e32 v5, v133, v5
	v_mul_f32_e32 v6, v134, v6
	v_mul_f32_e32 v7, v135, v7
	v_mul_f32_e32 v8, v136, v8
	v_mul_f32_e32 v9, v137, v9
	v_mul_f32_e32 v10, v138, v10
	v_mul_f32_e32 v11, v139, v11
	v_mul_f32_e32 v12, v140, v12
	v_mul_f32_e32 v13, v141, v13
	v_mul_f32_e32 v14, v142, v14
	v_mul_f32_e32 v15, v143, v15
	v_cvt_pk_bf16_f32 v148, v0, v1
	v_cvt_pk_bf16_f32 v149, v2, v3
	global_store_dwordx2 v145, v[148:149], s[42:43] offset:0
	v_cvt_pk_bf16_f32 v150, v4, v5
	v_cvt_pk_bf16_f32 v151, v6, v7
	global_store_dwordx2 v145, v[150:151], s[42:43] offset:512
	v_cvt_pk_bf16_f32 v152, v8, v9
	v_cvt_pk_bf16_f32 v153, v10, v11
	global_store_dwordx2 v145, v[152:153], s[42:43] offset:1024
	v_cvt_pk_bf16_f32 v154, v12, v13
	v_cvt_pk_bf16_f32 v155, v14, v15
	global_store_dwordx2 v145, v[154:155], s[42:43] offset:1536
	s_add_u32 s42, s42, 0x400000
	s_addc_u32 s43, s43, 0
	s_branch .Lxn_done
; __device__ __forceinline__ void phase_prologue(const Ctx& p, LAS unsigned char* lds) {
;     ...
;             } else {
; #pragma unroll
;                 for (int j = 0; j < 4; ++j) o8[64 * j] = (u32x2){0u, 0u}; }
; __global__ void __launch_bounds__(512) fwd_kernel(Params prm) {
;     ...
;     if (IN(0)) { phase_prologue(p, lds); } if (IN(0) && IN(1)) { if (lo < 0) grid.sync();   xcd_barrier(bar); }
.Lxn_zero:
	v_mov_b32_e32 v0, 0
	v_mov_b32_e32 v1, 0
	global_store_dwordx2 v145, v[0:1], s[42:43] offset:0
	global_store_dwordx2 v145, v[0:1], s[42:43] offset:512
	global_store_dwordx2 v145, v[0:1], s[42:43] offset:1024
	global_store_dwordx2 v145, v[0:1], s[42:43] offset:1536
.Lxn_done:
.LBB0_66:
	s_cmp_gt_i32 s37, 1
	s_cselect_b64 s[2:3], -1, 0
	s_and_b64 s[6:7], s[6:7], s[2:3]
	s_andn2_b64 vcc, exec, s[6:7]
	s_cbranch_vccnz .LBB0_132
	s_cmp_gt_i32 s36, -1
	s_cbranch_scc1 .LBB0_79
	v_lshrrev_b32_e32 v1, 20, v0
	v_lshrrev_b32_e32 v0, 10, v0
	v_or_b32_e32 v0, v0, v1
	s_movk_i32 s6, 0x3ff
	v_and_or_b32 v0, v0, s6, v180
	v_cmp_eq_u32_e32 vcc, 0, v0
	s_barrier
	s_and_saveexec_b64 s[6:7], vcc
	s_cbranch_execz .LBB0_78
	buffer_wbl2 sc1
	s_waitcnt vmcnt(0)
	s_load_dwordx2 s[4:5], s[4:5], 0x58
	v_mov_b32_e32 v2, 0
	s_mov_b64 s[8:9], exec
	v_mbcnt_lo_u32_b32 v1, s8, 0
	v_mbcnt_hi_u32_b32 v1, s9, v1
	s_waitcnt lgkmcnt(0)
	global_load_dword v0, v2, s[4:5] offset:40
	v_cmp_eq_u32_e32 vcc, 0, v1
	s_and_saveexec_b64 s[10:11], vcc
	s_cbranch_execz .LBB0_71
	s_bcnt1_i32_b64 s8, s[8:9]
	v_mov_b32_e32 v3, s8
	global_atomic_add v3, v2, v3, s[4:5] offset:32 sc0
